# in-proj GEMM: all per-phase s_setprio flips removed, one static s_setprio 1 for the wr==1 wave half (waves 4-7), reset after the phase
# speedup vs baseline: 1.0049x; 1.0022x over previous
;     __device__ __forceinline__ bool next(int i, Unit& u) const { if (i) return false; u.pm = pm; u.pn = pn; return true; }
;     __device__ __forceinline__ bool next(int i, Unit& u) const { if (i >= 5) return false; int t = i + rot; t = t >= 5 ? t - 5 : t; u.pm = pm; u.pn = e + 8 * t; return true; }
; template <class Epi, class Sched, bool ALIGN_EPI, bool SP2>
; __device__ __forceinline__ void gemm_phase(LAS unsigned char* lds, const Gemm g, const Sched& S, const Epi& E, int tid_in) {
;     ...
;     for (;;) {
;         const bool has_next = S.next(ui + 1, nxt);
;         const unsigned nA = has_next ? (unsigned)nxt.pm * tstepA : cA, nB = has_next ? (unsigned)nxt.pn * tstepB : cB;
;         for (int t = 0; t < nt; t += 2) {
;             const bool last = (t == nt - 2);
;             const unsigned a1 = cA + (unsigned)(t + 1) * kstep;
;             const unsigned a2 = last ? nA : cA + (unsigned)(t + 2) * kstep, b2 = last ? nB : cB + (unsigned)(t + 2) * kstep;
;             const unsigned a3 = a2 + kstep, b3 = b2 + kstep;
.LBB0_136:
	v_readlane_b32 s2, v255, 30
	v_readlane_b32 s3, v255, 31
	s_nop 0
	s_and_b64 vcc, exec, s[2:3]
	s_cbranch_vccnz .Lprio_skip
	s_setprio 1

; #define PG8_STAGE(bufoff, goff, voff) do { _Pragma("unroll") for (int _i = 0; _i < 2; ++_i) \
;         __builtin_amdgcn_raw_ptr_buffer_load_lds(R_##voff, (LAS void*)(lds + (bufoff) + ldsw + _i * 8192), 16, (int)(voff)[_i], (int)(goff), 0, 0); } while (0)
; #define PG8_WAIT_V(n) asm volatile("s_waitcnt vmcnt(" #n ")" ::: "memory")
; #define PG8_WAIT_L(n) asm volatile("s_waitcnt lgkmcnt(" #n ")" ::: "memory")
; #define PG8_BAR __builtin_amdgcn_s_barrier()
; #define PG8_SCHED __builtin_amdgcn_sched_barrier(0)
; template <class Epi, class Sched, bool ALIGN_EPI, bool SP2>
; __device__ __forceinline__ void gemm_phase(LAS unsigned char* lds, const Gemm g, const Sched& S, const Epi& E, int tid_in) {
;     ...
;             PG8_LDB(B0, 0, 0); PG8_LDB(B1, 0, 1); PG8_SCHED; PG8_LDA(At, 0, 0); PG8_STAGE(PG8_SA(1, 1), a1 + hstepA, voffA);
;             PG8_WAIT_V(8); PG8_WAIT_L(0); PG8_BAR; PG8_MMA(0, 0, At, B0); PG8_MMA(0, 1, At, B1); PG8_BAR; PG8_SCHED;
;             PG8_LDA(At, 0, 1); PG8_STAGE(PG8_SB(0, 0), b2, voffB); PG8_STAGE(PG8_SB(0, 1), b2 + hstepB, voffB); PG8_STAGE(PG8_SA(0, 0), a2, voffA);
;             PG8_WAIT_V(8); PG8_WAIT_L(0); PG8_BAR; PG8_MMA(1, 0, At, B0); PG8_MMA(1, 1, At, B1); PG8_BAR; PG8_SCHED;
.LBB0_137:
	v_add_u32_e32 v0, 0x10000, v193
	ds_read_b128 v[2:5], v0
	ds_read_b128 v[6:9], v0 offset:1024
	ds_read_b128 v[10:13], v0 offset:2048
	ds_read_b128 v[14:17], v0 offset:3072
	v_add_u32_e32 v0, 0x14000, v193
	ds_read_b128 v[18:21], v0
	ds_read_b128 v[22:25], v0 offset:1024
	ds_read_b128 v[26:29], v0 offset:2048
	ds_read_b128 v[30:33], v0 offset:3072
	s_add_i32 s11, s4, 0xfff00080
	s_cmp_eq_u32 s10, 60
	s_cselect_b32 s13, s3, s11
	s_cselect_b32 s12, s2, s5
	s_or_b32 s11, s13, 0x80
	s_mov_b32 m0, s8
	ds_read_b128 v[164:167], v194
	ds_read_b128 v[168:171], v194 offset:1024
	ds_read_b128 v[172:175], v194 offset:2048
	ds_read_b128 v[176:179], v194 offset:3072
	ds_read_b128 v[180:183], v194 offset:4096
	ds_read_b128 v[184:187], v194 offset:5120
	ds_read_b128 v[196:199], v194 offset:6144
	ds_read_b128 v[200:203], v194 offset:7168
	buffer_load_dwordx4 v115, s[40:43], s4 offen lds
	s_mov_b32 m0, s16
	s_nop 0
	buffer_load_dwordx4 v189, s[40:43], s4 offen lds
	s_waitcnt vmcnt(8)
	s_waitcnt lgkmcnt(0)
	s_barrier
	s_waitcnt lgkmcnt(7)
	v_mfma_f32_16x16x32_bf16 v[46:49], v[2:5], v[164:167], v[46:49]
	v_mfma_f32_16x16x32_bf16 v[42:45], v[10:13], v[164:167], v[42:45]
	s_waitcnt lgkmcnt(5)
	v_mfma_f32_16x16x32_bf16 v[160:163], v[2:5], v[172:175], v[160:163]
	v_mfma_f32_16x16x32_bf16 v[156:159], v[10:13], v[172:175], v[156:159]
	s_waitcnt lgkmcnt(3)
	v_mfma_f32_16x16x32_bf16 v[144:147], v[2:5], v[180:183], v[144:147]
	v_mfma_f32_16x16x32_bf16 v[140:143], v[10:13], v[180:183], v[140:143]
	s_waitcnt lgkmcnt(1)
	v_mfma_f32_16x16x32_bf16 v[62:65], v[2:5], v[196:199], v[62:65]
	v_mfma_f32_16x16x32_bf16 v[58:61], v[10:13], v[196:199], v[58:61]
	v_mfma_f32_16x16x32_bf16 v[46:49], v[6:9], v[168:171], v[46:49]
	v_mfma_f32_16x16x32_bf16 v[42:45], v[14:17], v[168:171], v[42:45]
	v_mfma_f32_16x16x32_bf16 v[160:163], v[6:9], v[176:179], v[160:163]
	v_mfma_f32_16x16x32_bf16 v[156:159], v[14:17], v[176:179], v[156:159]
	v_mfma_f32_16x16x32_bf16 v[144:147], v[6:9], v[184:187], v[144:147]
	v_mfma_f32_16x16x32_bf16 v[140:143], v[14:17], v[184:187], v[140:143]
	s_waitcnt lgkmcnt(0)
	v_mfma_f32_16x16x32_bf16 v[62:65], v[6:9], v[200:203], v[62:65]
	v_mfma_f32_16x16x32_bf16 v[58:61], v[14:17], v[200:203], v[58:61]
	v_mfma_f32_16x16x32_bf16 v[38:41], v[18:21], v[164:167], v[38:41]
	v_mfma_f32_16x16x32_bf16 v[34:37], v[26:29], v[164:167], v[34:37]
	v_mfma_f32_16x16x32_bf16 v[152:155], v[18:21], v[172:175], v[152:155]
	v_mfma_f32_16x16x32_bf16 v[148:151], v[26:29], v[172:175], v[148:151]
	v_mfma_f32_16x16x32_bf16 v[136:139], v[18:21], v[180:183], v[136:139]
	v_mfma_f32_16x16x32_bf16 v[132:135], v[26:29], v[180:183], v[132:135]
	v_mfma_f32_16x16x32_bf16 v[54:57], v[18:21], v[196:199], v[54:57]
	v_mfma_f32_16x16x32_bf16 v[50:53], v[26:29], v[196:199], v[50:53]
	v_mfma_f32_16x16x32_bf16 v[38:41], v[22:25], v[168:171], v[38:41]
	v_mfma_f32_16x16x32_bf16 v[34:37], v[30:33], v[168:171], v[34:37]
	v_mfma_f32_16x16x32_bf16 v[152:155], v[22:25], v[176:179], v[152:155]
	v_mfma_f32_16x16x32_bf16 v[148:151], v[30:33], v[176:179], v[148:151]
	v_mfma_f32_16x16x32_bf16 v[136:139], v[22:25], v[184:187], v[136:139]
	v_mfma_f32_16x16x32_bf16 v[132:135], v[30:33], v[184:187], v[132:135]
	v_mfma_f32_16x16x32_bf16 v[54:57], v[22:25], v[200:203], v[54:57]
	v_mfma_f32_16x16x32_bf16 v[50:53], v[30:33], v[200:203], v[50:53]
	s_barrier
	s_mov_b32 m0, s68
	s_mov_b32 s46, s42
	s_mov_b32 s47, s43
	ds_read_b128 v[164:167], v194 offset:16384
	ds_read_b128 v[168:171], v194 offset:17408
	ds_read_b128 v[172:175], v194 offset:18432
	ds_read_b128 v[176:179], v194 offset:19456
	ds_read_b128 v[180:183], v194 offset:20480
	ds_read_b128 v[184:187], v194 offset:21504
	ds_read_b128 v[196:199], v194 offset:22528
	ds_read_b128 v[200:203], v194 offset:23552
	buffer_load_dwordx4 v188, s[44:47], s12 offen lds
	s_mov_b32 m0, s69
	s_add_i32 s14, s12, 0x40000
	buffer_load_dwordx4 v190, s[44:47], s12 offen lds
	s_mov_b32 m0, s70
	s_nop 0
	buffer_load_dwordx4 v188, s[44:47], s14 offen lds
	s_mov_b32 m0, s72
	s_nop 0
	buffer_load_dwordx4 v190, s[44:47], s14 offen lds
	s_mov_b32 m0, s15
	s_nop 0
	buffer_load_dwordx4 v115, s[40:43], s13 offen lds
	s_mov_b32 m0, s73
	s_nop 0
	buffer_load_dwordx4 v189, s[40:43], s13 offen lds
	s_waitcnt vmcnt(8)
	s_waitcnt lgkmcnt(0)
	s_barrier
	s_waitcnt lgkmcnt(7)
	v_mfma_f32_16x16x32_bf16 v[128:131], v[2:5], v[164:167], v[128:131]
	v_mfma_f32_16x16x32_bf16 v[124:127], v[10:13], v[164:167], v[124:127]
	s_waitcnt lgkmcnt(5)
	v_mfma_f32_16x16x32_bf16 v[110:113], v[2:5], v[172:175], v[110:113]
	v_mfma_f32_16x16x32_bf16 v[106:109], v[10:13], v[172:175], v[106:109]
	s_waitcnt lgkmcnt(3)
	v_mfma_f32_16x16x32_bf16 v[94:97], v[2:5], v[180:183], v[94:97]
	v_mfma_f32_16x16x32_bf16 v[90:93], v[10:13], v[180:183], v[90:93]
	s_waitcnt lgkmcnt(1)
	v_mfma_f32_16x16x32_bf16 v[2:5], v[2:5], v[196:199], v[78:81]
	v_mfma_f32_16x16x32_bf16 v[128:131], v[6:9], v[168:171], v[128:131]
	v_mfma_f32_16x16x32_bf16 v[124:127], v[14:17], v[168:171], v[124:127]
	v_mfma_f32_16x16x32_bf16 v[110:113], v[6:9], v[176:179], v[110:113]
	v_mfma_f32_16x16x32_bf16 v[106:109], v[14:17], v[176:179], v[106:109]
	v_mfma_f32_16x16x32_bf16 v[94:97], v[6:9], v[184:187], v[94:97]
	v_mfma_f32_16x16x32_bf16 v[90:93], v[14:17], v[184:187], v[90:93]
	s_waitcnt lgkmcnt(0)
	v_mfma_f32_16x16x32_bf16 v[2:5], v[6:9], v[200:203], v[2:5]
	v_mfma_f32_16x16x32_bf16 v[6:9], v[10:13], v[196:199], v[74:77]
	v_mfma_f32_16x16x32_bf16 v[6:9], v[14:17], v[200:203], v[6:9]
	v_mfma_f32_16x16x32_bf16 v[74:77], v[18:21], v[172:175], v[102:105]
	v_mfma_f32_16x16x32_bf16 v[102:105], v[22:25], v[176:179], v[74:77]
	v_mfma_f32_16x16x32_bf16 v[74:77], v[26:29], v[172:175], v[98:101]
	v_mfma_f32_16x16x32_bf16 v[98:101], v[30:33], v[176:179], v[74:77]
	v_mfma_f32_16x16x32_bf16 v[74:77], v[18:21], v[180:183], v[86:89]
	v_mfma_f32_16x16x32_bf16 v[10:13], v[18:21], v[164:167], v[120:123]
	v_mfma_f32_16x16x32_bf16 v[86:89], v[22:25], v[184:187], v[74:77]
	v_mfma_f32_16x16x32_bf16 v[74:77], v[26:29], v[180:183], v[82:85]
	v_mfma_f32_16x16x32_bf16 v[18:21], v[18:21], v[196:199], v[70:73]
	v_mfma_f32_16x16x32_bf16 v[10:13], v[22:25], v[168:171], v[10:13]
	v_mfma_f32_16x16x32_bf16 v[14:17], v[26:29], v[164:167], v[116:119]
	v_mfma_f32_16x16x32_bf16 v[82:85], v[30:33], v[184:187], v[74:77]
	v_mfma_f32_16x16x32_bf16 v[18:21], v[22:25], v[200:203], v[18:21]
	v_mfma_f32_16x16x32_bf16 v[22:25], v[26:29], v[196:199], v[66:69]
	v_mfma_f32_16x16x32_bf16 v[14:17], v[30:33], v[168:171], v[14:17]
	v_mfma_f32_16x16x32_bf16 v[22:25], v[30:33], v[200:203], v[22:25]
	s_barrier
; #define PG8_STAGE(bufoff, goff, voff) do { _Pragma("unroll") for (int _i = 0; _i < 2; ++_i) \
;         __builtin_amdgcn_raw_ptr_buffer_load_lds(R_##voff, (LAS void*)(lds + (bufoff) + ldsw + _i * 8192), 16, (int)(voff)[_i], (int)(goff), 0, 0); } while (0)
; #define PG8_WAIT_V(n) asm volatile("s_waitcnt vmcnt(" #n ")" ::: "memory")
; #define PG8_WAIT_L(n) asm volatile("s_waitcnt lgkmcnt(" #n ")" ::: "memory")
; #define PG8_BAR __builtin_amdgcn_s_barrier()
; #define PG8_SCHED __builtin_amdgcn_sched_barrier(0)
; template <class Epi, class Sched, bool ALIGN_EPI, bool SP2>
; __device__ __forceinline__ void gemm_phase(LAS unsigned char* lds, const Gemm g, const Sched& S, const Epi& E, int tid_in) {
;     ...
;             PG8_LDB(B0, 1, 0); PG8_LDB(B1, 1, 1); PG8_SCHED; PG8_LDA(At, 1, 0); PG8_STAGE(PG8_SA(0, 1), a2 + hstepA, voffA);
;             PG8_WAIT_V(8); PG8_WAIT_L(0); PG8_BAR; PG8_MMA(0, 0, At, B0); PG8_MMA(0, 1, At, B1); PG8_BAR; PG8_SCHED;
;             PG8_LDA(At, 1, 1); PG8_STAGE(PG8_SB(1, 0), b3, voffB); PG8_STAGE(PG8_SB(1, 1), b3 + hstepB, voffB); PG8_STAGE(PG8_SA(1, 0), a3, voffA);
;             PG8_WAIT_V(8); PG8_WAIT_L(0); PG8_BAR; PG8_MMA(1, 0, At, B0); PG8_MMA(1, 1, At, B1); PG8_BAR; PG8_SCHED;
	v_add_u32_e32 v0, 0x18000, v193
	ds_read_b128 v[26:29], v0
	ds_read_b128 v[30:33], v0 offset:1024
	ds_read_b128 v[66:69], v0 offset:2048
	ds_read_b128 v[70:73], v0 offset:3072
	v_add_u32_e32 v0, 0x1c000, v193
	ds_read_b128 v[164:167], v0
	ds_read_b128 v[168:171], v0 offset:1024
	ds_read_b128 v[172:175], v0 offset:2048
	ds_read_b128 v[176:179], v0 offset:3072
	s_add_i32 s13, s13, 0x100000
	s_mov_b32 m0, s74
	ds_read_b128 v[74:77], v194 offset:32768
	ds_read_b128 v[78:81], v194 offset:33792
	ds_read_b128 v[116:119], v194 offset:34816
	ds_read_b128 v[120:123], v194 offset:35840
	ds_read_b128 v[180:183], v194 offset:36864
	ds_read_b128 v[184:187], v194 offset:37888
	ds_read_b128 v[196:199], v194 offset:38912
	ds_read_b128 v[200:203], v194 offset:39936
	buffer_load_dwordx4 v115, s[40:43], s13 offen lds
	s_mov_b32 m0, s75
	s_nop 0
	buffer_load_dwordx4 v189, s[40:43], s13 offen lds
	s_waitcnt vmcnt(8)
	s_waitcnt lgkmcnt(0)
	s_barrier
	s_waitcnt lgkmcnt(7)
	v_mfma_f32_16x16x32_bf16 v[46:49], v[26:29], v[74:77], v[46:49]
	v_mfma_f32_16x16x32_bf16 v[42:45], v[66:69], v[74:77], v[42:45]
	s_waitcnt lgkmcnt(5)
	v_mfma_f32_16x16x32_bf16 v[160:163], v[26:29], v[116:119], v[160:163]
	v_mfma_f32_16x16x32_bf16 v[156:159], v[66:69], v[116:119], v[156:159]
	s_waitcnt lgkmcnt(3)
	v_mfma_f32_16x16x32_bf16 v[144:147], v[26:29], v[180:183], v[144:147]
	v_mfma_f32_16x16x32_bf16 v[140:143], v[66:69], v[180:183], v[140:143]
	s_waitcnt lgkmcnt(1)
	v_mfma_f32_16x16x32_bf16 v[62:65], v[26:29], v[196:199], v[62:65]
	v_mfma_f32_16x16x32_bf16 v[58:61], v[66:69], v[196:199], v[58:61]
	v_mfma_f32_16x16x32_bf16 v[46:49], v[30:33], v[78:81], v[46:49]
	v_mfma_f32_16x16x32_bf16 v[42:45], v[70:73], v[78:81], v[42:45]
	v_mfma_f32_16x16x32_bf16 v[160:163], v[30:33], v[120:123], v[160:163]
	v_mfma_f32_16x16x32_bf16 v[156:159], v[70:73], v[120:123], v[156:159]
	v_mfma_f32_16x16x32_bf16 v[144:147], v[30:33], v[184:187], v[144:147]
	v_mfma_f32_16x16x32_bf16 v[140:143], v[70:73], v[184:187], v[140:143]
	s_waitcnt lgkmcnt(0)
	v_mfma_f32_16x16x32_bf16 v[62:65], v[30:33], v[200:203], v[62:65]
	v_mfma_f32_16x16x32_bf16 v[58:61], v[70:73], v[200:203], v[58:61]
	v_mfma_f32_16x16x32_bf16 v[38:41], v[164:167], v[74:77], v[38:41]
	v_mfma_f32_16x16x32_bf16 v[34:37], v[172:175], v[74:77], v[34:37]
	v_mfma_f32_16x16x32_bf16 v[74:77], v[164:167], v[116:119], v[152:155]
	v_mfma_f32_16x16x32_bf16 v[152:155], v[168:171], v[120:123], v[74:77]
	v_mfma_f32_16x16x32_bf16 v[74:77], v[172:175], v[116:119], v[148:151]
	v_mfma_f32_16x16x32_bf16 v[148:151], v[176:179], v[120:123], v[74:77]
	v_mfma_f32_16x16x32_bf16 v[74:77], v[164:167], v[180:183], v[136:139]
	v_mfma_f32_16x16x32_bf16 v[136:139], v[168:171], v[184:187], v[74:77]
	v_mfma_f32_16x16x32_bf16 v[74:77], v[172:175], v[180:183], v[132:135]
	v_mfma_f32_16x16x32_bf16 v[54:57], v[164:167], v[196:199], v[54:57]
	v_mfma_f32_16x16x32_bf16 v[50:53], v[172:175], v[196:199], v[50:53]
	v_mfma_f32_16x16x32_bf16 v[38:41], v[168:171], v[78:81], v[38:41]
	v_mfma_f32_16x16x32_bf16 v[34:37], v[176:179], v[78:81], v[34:37]
	v_mfma_f32_16x16x32_bf16 v[132:135], v[176:179], v[184:187], v[74:77]
	v_mfma_f32_16x16x32_bf16 v[54:57], v[168:171], v[200:203], v[54:57]
	v_mfma_f32_16x16x32_bf16 v[50:53], v[176:179], v[200:203], v[50:53]
	s_barrier
	s_mov_b32 m0, s85
	s_or_b32 s13, s12, 0x80
	ds_read_b128 v[116:119], v194 offset:49152
	ds_read_b128 v[180:183], v194 offset:50176
	ds_read_b128 v[184:187], v194 offset:51200
	ds_read_b128 v[196:199], v194 offset:52224
	ds_read_b128 v[200:203], v194 offset:53248
	ds_read_b128 v[204:207], v194 offset:54272
	ds_read_b128 v[208:211], v194 offset:55296
	ds_read_b128 v[220:223], v194 offset:56320
	buffer_load_dwordx4 v188, s[44:47], s13 offen lds
	s_mov_b32 m0, s93
	s_add_i32 s12, s12, 0x40080
	buffer_load_dwordx4 v190, s[44:47], s13 offen lds
	s_mov_b32 m0, s67
	s_nop 0
	buffer_load_dwordx4 v188, s[44:47], s12 offen lds
	s_mov_b32 m0, s49
	s_nop 0
	buffer_load_dwordx4 v190, s[44:47], s12 offen lds
	s_mov_b32 m0, s94
	s_nop 0
	buffer_load_dwordx4 v115, s[40:43], s11 offen lds
	s_mov_b32 m0, s95
	s_nop 0
	buffer_load_dwordx4 v189, s[40:43], s11 offen lds
	s_waitcnt vmcnt(8)
	s_waitcnt lgkmcnt(0)
	s_barrier
	s_waitcnt lgkmcnt(7)
	v_mfma_f32_16x16x32_bf16 v[74:77], v[26:29], v[116:119], v[128:131]
	s_waitcnt lgkmcnt(6)
	v_mfma_f32_16x16x32_bf16 v[128:131], v[30:33], v[180:183], v[74:77]
	v_mfma_f32_16x16x32_bf16 v[74:77], v[66:69], v[116:119], v[124:127]
	v_mfma_f32_16x16x32_bf16 v[124:127], v[70:73], v[180:183], v[74:77]
	s_waitcnt lgkmcnt(5)
	v_mfma_f32_16x16x32_bf16 v[74:77], v[26:29], v[184:187], v[110:113]
	s_waitcnt lgkmcnt(4)
	v_mfma_f32_16x16x32_bf16 v[110:113], v[30:33], v[196:199], v[74:77]
	v_mfma_f32_16x16x32_bf16 v[74:77], v[66:69], v[184:187], v[106:109]
	v_mfma_f32_16x16x32_bf16 v[106:109], v[70:73], v[196:199], v[74:77]
	s_waitcnt lgkmcnt(3)
	v_mfma_f32_16x16x32_bf16 v[74:77], v[26:29], v[200:203], v[94:97]
	s_waitcnt lgkmcnt(1)
	v_mfma_f32_16x16x32_bf16 v[2:5], v[26:29], v[208:211], v[2:5]
	v_mfma_f32_16x16x32_bf16 v[94:97], v[30:33], v[204:207], v[74:77]
	v_mfma_f32_16x16x32_bf16 v[74:77], v[66:69], v[200:203], v[90:93]
	s_waitcnt lgkmcnt(0)
	v_mfma_f32_16x16x32_bf16 v[78:81], v[30:33], v[220:223], v[2:5]
	v_mfma_f32_16x16x32_bf16 v[2:5], v[66:69], v[208:211], v[6:9]
	v_mfma_f32_16x16x32_bf16 v[90:93], v[70:73], v[204:207], v[74:77]
	v_mfma_f32_16x16x32_bf16 v[74:77], v[70:73], v[220:223], v[2:5]
	v_mfma_f32_16x16x32_bf16 v[2:5], v[164:167], v[116:119], v[10:13]
	v_mfma_f32_16x16x32_bf16 v[120:123], v[168:171], v[180:183], v[2:5]
	v_mfma_f32_16x16x32_bf16 v[2:5], v[172:175], v[116:119], v[14:17]
	v_mfma_f32_16x16x32_bf16 v[116:119], v[176:179], v[180:183], v[2:5]
	v_mfma_f32_16x16x32_bf16 v[2:5], v[164:167], v[184:187], v[102:105]
	v_mfma_f32_16x16x32_bf16 v[102:105], v[168:171], v[196:199], v[2:5]
	v_mfma_f32_16x16x32_bf16 v[2:5], v[172:175], v[184:187], v[98:101]
	v_mfma_f32_16x16x32_bf16 v[98:101], v[176:179], v[196:199], v[2:5]
	v_mfma_f32_16x16x32_bf16 v[2:5], v[164:167], v[200:203], v[86:89]
	v_mfma_f32_16x16x32_bf16 v[86:89], v[168:171], v[204:207], v[2:5]
	v_mfma_f32_16x16x32_bf16 v[2:5], v[172:175], v[200:203], v[82:85]
	v_mfma_f32_16x16x32_bf16 v[82:85], v[176:179], v[204:207], v[2:5]
	v_mfma_f32_16x16x32_bf16 v[2:5], v[164:167], v[208:211], v[18:21]
	v_mfma_f32_16x16x32_bf16 v[70:73], v[168:171], v[220:223], v[2:5]
	v_mfma_f32_16x16x32_bf16 v[2:5], v[172:175], v[208:211], v[22:25]
	v_mfma_f32_16x16x32_bf16 v[66:69], v[176:179], v[220:223], v[2:5]
	s_barrier
	s_add_i32 s10, s10, 2
	s_addk_i32 s4, 0x100
	s_addk_i32 s5, 0x100
	s_cmp_gt_u32 s10, 61
	s_cbranch_scc0 .LBB0_137
	v_readlane_b32 s2, v255, 30
	v_readlane_b32 s3, v255, 31
	s_and_b64 vcc, exec, s[2:3]
	s_cbranch_vccz .LBB0_140
	s_barrier

;     __device__ __forceinline__ bool next(int i, Unit& u) const { if (i) return false; u.pm = pm; u.pn = pn; return true; }
; #define PG8_WAIT_V(n) asm volatile("s_waitcnt vmcnt(" #n ")" ::: "memory")
; #define PG8_BAR __builtin_amdgcn_s_barrier()
;     __device__ __forceinline__ bool next(int i, Unit& u) const { if (i >= 5) return false; int t = i + rot; t = t >= 5 ? t - 5 : t; u.pm = pm; u.pn = e + 8 * t; return true; }
;     __host__ __device__ bool next(int i, Unit& u) const {
;         const long L = (long)i * G + c; if (L >= nwg) return false;
;         int wgid = (int)L; { const int q = nwg / NXCD, r = nwg % NXCD, xcd = wgid % NXCD, off = wgid / NXCD; wgid = (xcd < r ? xcd * (q + 1) : r * (q + 1) + (xcd - r) * q) + off; }
;         const int nig = WGM * nN, gid = wgid / nig, fm = gid * WGM, gsz = (nM - fm) < WGM ? (nM - fm) : WGM;
;         u.pm = fm + ((wgid % nig) % gsz); u.pn = (wgid % nig) / gsz; return true;
; template <class Epi, class Sched, bool ALIGN_EPI, bool SP2>
; __device__ __forceinline__ void gemm_phase(LAS unsigned char* lds, const Gemm g, const Sched& S, const Epi& E, int tid_in) {
;     ...
;     PG8_WAIT_V(0);
;     if constexpr (!ALIGN_EPI) { if (wr == 0) PG8_BAR; }
;     PG8_BAR;
.LBB0_313:
	s_setprio 0
	s_waitcnt vmcnt(0)
	s_cmpk_lt_i32 s65, 0x100
	v_readlane_b32 s30, v255, 13
	v_readlane_b32 s52, v255, 26
	s_cselect_b64 s[2:3], -1, 0
	s_cmpk_gt_i32 s65, 0xff
	s_mov_b32 s4, 0
	v_readlane_b32 s88, v255, 1
	v_readlane_b32 s31, v255, 14
	v_readlane_b32 s53, v255, 27
	v_readlane_b32 s54, v255, 28
	v_readlane_b32 s55, v255, 29
	v_readlane_b32 s89, v255, 15
	v_readlane_b32 s91, v255, 16
	v_readlane_b32 s95, v255, 17
	s_mov_b64 s[78:79], s[62:63]
	v_readlane_b32 s93, v255, 36
	s_barrier
	s_cbranch_scc1 .LBB0_319
	s_ashr_i32 s4, s65, 31
	s_lshr_b32 s4, s4, 29
	s_add_i32 s6, s65, s4
	s_and_b32 s4, s6, -8
	s_sub_i32 s7, s65, s4
	s_cmp_gt_i32 s7, -1
	s_mov_b64 s[4:5], -1
	s_cbranch_scc0 .LBB0_316
	s_lshl_b32 s8, s7, 5
	s_mov_b64 s[4:5], 0
